# ctx_resid_gemm K loop fully unrolled and software-pipelined (4 load sets in flight) on top of v12
# speedup vs baseline: 1.0273x; 1.0020x over previous
.LBB0_403:
	s_ashr_i32 s11, s10, 31
	s_lshl_b64 s[20:21], s[10:11], 1
	v_lshl_add_u64 v[140:141], v[48:49], 0, s[20:21]
	s_mov_b32 s99, 0
	s_mov_b32 s98, s13
	v_lshl_add_u64 v[142:143], v[140:141], 0, s[98:99]
	s_mov_b32 s98, s14
	v_lshl_add_u64 v[144:145], v[140:141], 0, s[98:99]
	s_mov_b32 s98, s15
	v_lshl_add_u64 v[146:147], v[140:141], 0, s[98:99]
	v_lshl_add_u64 v[148:149], v[36:37], 0, s[20:21]
	v_lshl_add_u64 v[150:151], v[148:149], 0, v[46:47]
	v_lshl_add_u64 v[148:149], v[148:149], 0, v[44:45]
	global_load_dwordx4 v[180:183], v[140:141], off
	global_load_dwordx4 v[184:187], v[148:149], off
	global_load_dwordx4 v[188:191], v[150:151], off
	global_load_dwordx4 v[192:195], v[142:143], off
	global_load_dwordx4 v[196:199], v[144:145], off
	global_load_dwordx4 v[200:203], v[146:147], off
	global_load_dwordx4 v[204:207], v[140:141], off offset:512
	global_load_dwordx4 v[208:211], v[148:149], off offset:512
	global_load_dwordx4 v[212:215], v[150:151], off offset:512
	global_load_dwordx4 v[216:219], v[142:143], off offset:512
	global_load_dwordx4 v[220:223], v[144:145], off offset:512
	global_load_dwordx4 v[224:227], v[146:147], off offset:512
	global_load_dwordx4 v[116:119], v[140:141], off offset:1024
	global_load_dwordx4 v[120:123], v[148:149], off offset:1024
	global_load_dwordx4 v[124:127], v[150:151], off offset:1024
	global_load_dwordx4 v[128:131], v[142:143], off offset:1024
	global_load_dwordx4 v[132:135], v[144:145], off offset:1024
	global_load_dwordx4 v[136:139], v[146:147], off offset:1024
	global_load_dwordx4 v[56:59], v[140:141], off offset:1536
	global_load_dwordx4 v[60:63], v[148:149], off offset:1536
	global_load_dwordx4 v[64:67], v[150:151], off offset:1536
	global_load_dwordx4 v[68:71], v[142:143], off offset:1536
	global_load_dwordx4 v[72:75], v[144:145], off offset:1536
	global_load_dwordx4 v[76:79], v[146:147], off offset:1536
	s_waitcnt vmcnt(18)
	v_mfma_f32_16x16x32_bf16 v[26:29], v[192:195], v[184:187], v[26:29]
	v_mfma_f32_16x16x32_bf16 v[30:33], v[180:183], v[184:187], v[30:33]
	v_mfma_f32_16x16x32_bf16 v[14:17], v[180:183], v[188:191], v[14:17]
	v_mfma_f32_16x16x32_bf16 v[22:25], v[196:199], v[184:187], v[22:25]
	v_mfma_f32_16x16x32_bf16 v[10:13], v[192:195], v[188:191], v[10:13]
	v_mfma_f32_16x16x32_bf16 v[6:9], v[196:199], v[188:191], v[6:9]
	v_mfma_f32_16x16x32_bf16 v[18:21], v[200:203], v[184:187], v[18:21]
	v_mfma_f32_16x16x32_bf16 v[2:5], v[200:203], v[188:191], v[2:5]
	global_load_dwordx4 v[180:183], v[140:141], off offset:2048
	global_load_dwordx4 v[184:187], v[148:149], off offset:2048
	global_load_dwordx4 v[188:191], v[150:151], off offset:2048
	global_load_dwordx4 v[192:195], v[142:143], off offset:2048
	global_load_dwordx4 v[196:199], v[144:145], off offset:2048
	global_load_dwordx4 v[200:203], v[146:147], off offset:2048
	s_waitcnt vmcnt(18)
	v_mfma_f32_16x16x32_bf16 v[26:29], v[216:219], v[208:211], v[26:29]
	v_mfma_f32_16x16x32_bf16 v[30:33], v[204:207], v[208:211], v[30:33]
	v_mfma_f32_16x16x32_bf16 v[14:17], v[204:207], v[212:215], v[14:17]
	v_mfma_f32_16x16x32_bf16 v[22:25], v[220:223], v[208:211], v[22:25]
	v_mfma_f32_16x16x32_bf16 v[10:13], v[216:219], v[212:215], v[10:13]
	v_mfma_f32_16x16x32_bf16 v[6:9], v[220:223], v[212:215], v[6:9]
	v_mfma_f32_16x16x32_bf16 v[18:21], v[224:227], v[208:211], v[18:21]
	v_mfma_f32_16x16x32_bf16 v[2:5], v[224:227], v[212:215], v[2:5]
	global_load_dwordx4 v[204:207], v[140:141], off offset:2560
	global_load_dwordx4 v[208:211], v[148:149], off offset:2560
	global_load_dwordx4 v[212:215], v[150:151], off offset:2560
	global_load_dwordx4 v[216:219], v[142:143], off offset:2560
	global_load_dwordx4 v[220:223], v[144:145], off offset:2560
	global_load_dwordx4 v[224:227], v[146:147], off offset:2560
	s_waitcnt vmcnt(18)
	v_mfma_f32_16x16x32_bf16 v[26:29], v[128:131], v[120:123], v[26:29]
	v_mfma_f32_16x16x32_bf16 v[30:33], v[116:119], v[120:123], v[30:33]
	v_mfma_f32_16x16x32_bf16 v[14:17], v[116:119], v[124:127], v[14:17]
	v_mfma_f32_16x16x32_bf16 v[22:25], v[132:135], v[120:123], v[22:25]
	v_mfma_f32_16x16x32_bf16 v[10:13], v[128:131], v[124:127], v[10:13]
	v_mfma_f32_16x16x32_bf16 v[6:9], v[132:135], v[124:127], v[6:9]
	v_mfma_f32_16x16x32_bf16 v[18:21], v[136:139], v[120:123], v[18:21]
	v_mfma_f32_16x16x32_bf16 v[2:5], v[136:139], v[124:127], v[2:5]
	global_load_dwordx4 v[116:119], v[140:141], off offset:3072
	global_load_dwordx4 v[120:123], v[148:149], off offset:3072
	global_load_dwordx4 v[124:127], v[150:151], off offset:3072
	global_load_dwordx4 v[128:131], v[142:143], off offset:3072
	global_load_dwordx4 v[132:135], v[144:145], off offset:3072
	global_load_dwordx4 v[136:139], v[146:147], off offset:3072
	s_waitcnt vmcnt(18)
	v_mfma_f32_16x16x32_bf16 v[26:29], v[68:71], v[60:63], v[26:29]
	v_mfma_f32_16x16x32_bf16 v[30:33], v[56:59], v[60:63], v[30:33]
	v_mfma_f32_16x16x32_bf16 v[14:17], v[56:59], v[64:67], v[14:17]
	v_mfma_f32_16x16x32_bf16 v[22:25], v[72:75], v[60:63], v[22:25]
	v_mfma_f32_16x16x32_bf16 v[10:13], v[68:71], v[64:67], v[10:13]
	v_mfma_f32_16x16x32_bf16 v[6:9], v[72:75], v[64:67], v[6:9]
	v_mfma_f32_16x16x32_bf16 v[18:21], v[76:79], v[60:63], v[18:21]
	v_mfma_f32_16x16x32_bf16 v[2:5], v[76:79], v[64:67], v[2:5]
	global_load_dwordx4 v[56:59], v[140:141], off offset:3584
	global_load_dwordx4 v[60:63], v[148:149], off offset:3584
	global_load_dwordx4 v[64:67], v[150:151], off offset:3584
	global_load_dwordx4 v[68:71], v[142:143], off offset:3584
	global_load_dwordx4 v[72:75], v[144:145], off offset:3584
	global_load_dwordx4 v[76:79], v[146:147], off offset:3584
	s_waitcnt vmcnt(18)
	v_mfma_f32_16x16x32_bf16 v[26:29], v[192:195], v[184:187], v[26:29]
	v_mfma_f32_16x16x32_bf16 v[30:33], v[180:183], v[184:187], v[30:33]
	v_mfma_f32_16x16x32_bf16 v[14:17], v[180:183], v[188:191], v[14:17]
	v_mfma_f32_16x16x32_bf16 v[22:25], v[196:199], v[184:187], v[22:25]
	v_mfma_f32_16x16x32_bf16 v[10:13], v[192:195], v[188:191], v[10:13]
	v_mfma_f32_16x16x32_bf16 v[6:9], v[196:199], v[188:191], v[6:9]
	v_mfma_f32_16x16x32_bf16 v[18:21], v[200:203], v[184:187], v[18:21]
	v_mfma_f32_16x16x32_bf16 v[2:5], v[200:203], v[188:191], v[2:5]
	s_movk_i32 s98, 0x1000
	v_lshl_add_u64 v[140:141], v[140:141], 0, s[98:99]
	v_lshl_add_u64 v[142:143], v[142:143], 0, s[98:99]
	v_lshl_add_u64 v[144:145], v[144:145], 0, s[98:99]
	v_lshl_add_u64 v[146:147], v[146:147], 0, s[98:99]
	v_lshl_add_u64 v[148:149], v[148:149], 0, s[98:99]
	v_lshl_add_u64 v[150:151], v[150:151], 0, s[98:99]
	global_load_dwordx4 v[180:183], v[140:141], off
	global_load_dwordx4 v[184:187], v[148:149], off
	global_load_dwordx4 v[188:191], v[150:151], off
	global_load_dwordx4 v[192:195], v[142:143], off
	global_load_dwordx4 v[196:199], v[144:145], off
	global_load_dwordx4 v[200:203], v[146:147], off
	s_waitcnt vmcnt(18)
	v_mfma_f32_16x16x32_bf16 v[26:29], v[216:219], v[208:211], v[26:29]
	v_mfma_f32_16x16x32_bf16 v[30:33], v[204:207], v[208:211], v[30:33]
	v_mfma_f32_16x16x32_bf16 v[14:17], v[204:207], v[212:215], v[14:17]
	v_mfma_f32_16x16x32_bf16 v[22:25], v[220:223], v[208:211], v[22:25]
	v_mfma_f32_16x16x32_bf16 v[10:13], v[216:219], v[212:215], v[10:13]
	v_mfma_f32_16x16x32_bf16 v[6:9], v[220:223], v[212:215], v[6:9]
	v_mfma_f32_16x16x32_bf16 v[18:21], v[224:227], v[208:211], v[18:21]
	v_mfma_f32_16x16x32_bf16 v[2:5], v[224:227], v[212:215], v[2:5]
	global_load_dwordx4 v[204:207], v[140:141], off offset:512
	global_load_dwordx4 v[208:211], v[148:149], off offset:512
	global_load_dwordx4 v[212:215], v[150:151], off offset:512
	global_load_dwordx4 v[216:219], v[142:143], off offset:512
	global_load_dwordx4 v[220:223], v[144:145], off offset:512
	global_load_dwordx4 v[224:227], v[146:147], off offset:512
	s_waitcnt vmcnt(18)
	v_mfma_f32_16x16x32_bf16 v[26:29], v[128:131], v[120:123], v[26:29]
	v_mfma_f32_16x16x32_bf16 v[30:33], v[116:119], v[120:123], v[30:33]
	v_mfma_f32_16x16x32_bf16 v[14:17], v[116:119], v[124:127], v[14:17]
	v_mfma_f32_16x16x32_bf16 v[22:25], v[132:135], v[120:123], v[22:25]
	v_mfma_f32_16x16x32_bf16 v[10:13], v[128:131], v[124:127], v[10:13]
	v_mfma_f32_16x16x32_bf16 v[6:9], v[132:135], v[124:127], v[6:9]
	v_mfma_f32_16x16x32_bf16 v[18:21], v[136:139], v[120:123], v[18:21]
	v_mfma_f32_16x16x32_bf16 v[2:5], v[136:139], v[124:127], v[2:5]
	global_load_dwordx4 v[116:119], v[140:141], off offset:1024
	global_load_dwordx4 v[120:123], v[148:149], off offset:1024
	global_load_dwordx4 v[124:127], v[150:151], off offset:1024
	global_load_dwordx4 v[128:131], v[142:143], off offset:1024
	global_load_dwordx4 v[132:135], v[144:145], off offset:1024
	global_load_dwordx4 v[136:139], v[146:147], off offset:1024
	s_waitcnt vmcnt(18)
	v_mfma_f32_16x16x32_bf16 v[26:29], v[68:71], v[60:63], v[26:29]
	v_mfma_f32_16x16x32_bf16 v[30:33], v[56:59], v[60:63], v[30:33]
	v_mfma_f32_16x16x32_bf16 v[14:17], v[56:59], v[64:67], v[14:17]
	v_mfma_f32_16x16x32_bf16 v[22:25], v[72:75], v[60:63], v[22:25]
	v_mfma_f32_16x16x32_bf16 v[10:13], v[68:71], v[64:67], v[10:13]
	v_mfma_f32_16x16x32_bf16 v[6:9], v[72:75], v[64:67], v[6:9]
	v_mfma_f32_16x16x32_bf16 v[18:21], v[76:79], v[60:63], v[18:21]
	v_mfma_f32_16x16x32_bf16 v[2:5], v[76:79], v[64:67], v[2:5]
	s_waitcnt vmcnt(12)
	v_mfma_f32_16x16x32_bf16 v[26:29], v[192:195], v[184:187], v[26:29]
	v_mfma_f32_16x16x32_bf16 v[30:33], v[180:183], v[184:187], v[30:33]
	v_mfma_f32_16x16x32_bf16 v[14:17], v[180:183], v[188:191], v[14:17]
	v_mfma_f32_16x16x32_bf16 v[22:25], v[196:199], v[184:187], v[22:25]
	v_mfma_f32_16x16x32_bf16 v[10:13], v[192:195], v[188:191], v[10:13]
	v_mfma_f32_16x16x32_bf16 v[6:9], v[196:199], v[188:191], v[6:9]
	v_mfma_f32_16x16x32_bf16 v[18:21], v[200:203], v[184:187], v[18:21]
	v_mfma_f32_16x16x32_bf16 v[2:5], v[200:203], v[188:191], v[2:5]
	s_waitcnt vmcnt(6)
	v_mfma_f32_16x16x32_bf16 v[26:29], v[216:219], v[208:211], v[26:29]
	v_mfma_f32_16x16x32_bf16 v[30:33], v[204:207], v[208:211], v[30:33]
	v_mfma_f32_16x16x32_bf16 v[14:17], v[204:207], v[212:215], v[14:17]
	v_mfma_f32_16x16x32_bf16 v[22:25], v[220:223], v[208:211], v[22:25]
	v_mfma_f32_16x16x32_bf16 v[10:13], v[216:219], v[212:215], v[10:13]
	v_mfma_f32_16x16x32_bf16 v[6:9], v[220:223], v[212:215], v[6:9]
	v_mfma_f32_16x16x32_bf16 v[18:21], v[224:227], v[208:211], v[18:21]
	v_mfma_f32_16x16x32_bf16 v[2:5], v[224:227], v[212:215], v[2:5]
	s_waitcnt vmcnt(0)
	v_mfma_f32_16x16x32_bf16 v[26:29], v[128:131], v[120:123], v[26:29]
	v_mfma_f32_16x16x32_bf16 v[30:33], v[116:119], v[120:123], v[30:33]
	v_mfma_f32_16x16x32_bf16 v[14:17], v[116:119], v[124:127], v[14:17]
	v_mfma_f32_16x16x32_bf16 v[22:25], v[132:135], v[120:123], v[22:25]
	v_mfma_f32_16x16x32_bf16 v[10:13], v[128:131], v[124:127], v[10:13]
	v_mfma_f32_16x16x32_bf16 v[6:9], v[132:135], v[124:127], v[6:9]
	v_mfma_f32_16x16x32_bf16 v[18:21], v[136:139], v[120:123], v[18:21]
	v_mfma_f32_16x16x32_bf16 v[2:5], v[136:139], v[124:127], v[2:5]
	s_nop 1
	s_branch .LBB0_400

.LBB0_1113:
	s_ashr_i32 s11, s10, 31
	s_lshl_b64 s[18:19], s[10:11], 1
	v_lshl_add_u64 v[140:141], v[46:47], 0, s[18:19]
	s_mov_b32 s99, 0
	s_mov_b32 s98, s12
	v_lshl_add_u64 v[142:143], v[140:141], 0, s[98:99]
	s_mov_b32 s98, s13
	v_lshl_add_u64 v[144:145], v[140:141], 0, s[98:99]
	s_mov_b32 s98, s14
	v_lshl_add_u64 v[146:147], v[140:141], 0, s[98:99]
	v_lshl_add_u64 v[148:149], v[36:37], 0, s[18:19]
	v_lshl_add_u64 v[150:151], v[148:149], 0, v[44:45]
	v_lshl_add_u64 v[148:149], v[148:149], 0, v[42:43]
	global_load_dwordx4 v[180:183], v[140:141], off
	global_load_dwordx4 v[184:187], v[148:149], off
	global_load_dwordx4 v[188:191], v[150:151], off
	global_load_dwordx4 v[192:195], v[142:143], off
	global_load_dwordx4 v[196:199], v[144:145], off
	global_load_dwordx4 v[200:203], v[146:147], off
	global_load_dwordx4 v[204:207], v[140:141], off offset:512
	global_load_dwordx4 v[208:211], v[148:149], off offset:512
	global_load_dwordx4 v[212:215], v[150:151], off offset:512
	global_load_dwordx4 v[216:219], v[142:143], off offset:512
	global_load_dwordx4 v[220:223], v[144:145], off offset:512
	global_load_dwordx4 v[224:227], v[146:147], off offset:512
	global_load_dwordx4 v[116:119], v[140:141], off offset:1024
	global_load_dwordx4 v[120:123], v[148:149], off offset:1024
	global_load_dwordx4 v[124:127], v[150:151], off offset:1024
	global_load_dwordx4 v[128:131], v[142:143], off offset:1024
	global_load_dwordx4 v[132:135], v[144:145], off offset:1024
	global_load_dwordx4 v[136:139], v[146:147], off offset:1024
	global_load_dwordx4 v[56:59], v[140:141], off offset:1536
	global_load_dwordx4 v[60:63], v[148:149], off offset:1536
	global_load_dwordx4 v[64:67], v[150:151], off offset:1536
	global_load_dwordx4 v[68:71], v[142:143], off offset:1536
	global_load_dwordx4 v[72:75], v[144:145], off offset:1536
	global_load_dwordx4 v[76:79], v[146:147], off offset:1536
	s_waitcnt vmcnt(18)
	v_mfma_f32_16x16x32_bf16 v[26:29], v[192:195], v[184:187], v[26:29]
	v_mfma_f32_16x16x32_bf16 v[30:33], v[180:183], v[184:187], v[30:33]
	v_mfma_f32_16x16x32_bf16 v[14:17], v[180:183], v[188:191], v[14:17]
	v_mfma_f32_16x16x32_bf16 v[22:25], v[196:199], v[184:187], v[22:25]
	v_mfma_f32_16x16x32_bf16 v[10:13], v[192:195], v[188:191], v[10:13]
	v_mfma_f32_16x16x32_bf16 v[6:9], v[196:199], v[188:191], v[6:9]
	v_mfma_f32_16x16x32_bf16 v[18:21], v[200:203], v[184:187], v[18:21]
	v_mfma_f32_16x16x32_bf16 v[2:5], v[200:203], v[188:191], v[2:5]
	s_waitcnt vmcnt(12)
	v_mfma_f32_16x16x32_bf16 v[26:29], v[216:219], v[208:211], v[26:29]
	v_mfma_f32_16x16x32_bf16 v[30:33], v[204:207], v[208:211], v[30:33]
	v_mfma_f32_16x16x32_bf16 v[14:17], v[204:207], v[212:215], v[14:17]
	v_mfma_f32_16x16x32_bf16 v[22:25], v[220:223], v[208:211], v[22:25]
	v_mfma_f32_16x16x32_bf16 v[10:13], v[216:219], v[212:215], v[10:13]
	v_mfma_f32_16x16x32_bf16 v[6:9], v[220:223], v[212:215], v[6:9]
	v_mfma_f32_16x16x32_bf16 v[18:21], v[224:227], v[208:211], v[18:21]
	v_mfma_f32_16x16x32_bf16 v[2:5], v[224:227], v[212:215], v[2:5]
	s_waitcnt vmcnt(6)
	v_mfma_f32_16x16x32_bf16 v[26:29], v[128:131], v[120:123], v[26:29]
	v_mfma_f32_16x16x32_bf16 v[30:33], v[116:119], v[120:123], v[30:33]
	v_mfma_f32_16x16x32_bf16 v[14:17], v[116:119], v[124:127], v[14:17]
	v_mfma_f32_16x16x32_bf16 v[22:25], v[132:135], v[120:123], v[22:25]
	v_mfma_f32_16x16x32_bf16 v[10:13], v[128:131], v[124:127], v[10:13]
	v_mfma_f32_16x16x32_bf16 v[6:9], v[132:135], v[124:127], v[6:9]
	v_mfma_f32_16x16x32_bf16 v[18:21], v[136:139], v[120:123], v[18:21]
	v_mfma_f32_16x16x32_bf16 v[2:5], v[136:139], v[124:127], v[2:5]
	s_waitcnt vmcnt(0)
	v_mfma_f32_16x16x32_bf16 v[26:29], v[68:71], v[60:63], v[26:29]
	v_mfma_f32_16x16x32_bf16 v[30:33], v[56:59], v[60:63], v[30:33]
	v_mfma_f32_16x16x32_bf16 v[14:17], v[56:59], v[64:67], v[14:17]
	v_mfma_f32_16x16x32_bf16 v[22:25], v[72:75], v[60:63], v[22:25]
	v_mfma_f32_16x16x32_bf16 v[10:13], v[68:71], v[64:67], v[10:13]
	v_mfma_f32_16x16x32_bf16 v[6:9], v[72:75], v[64:67], v[6:9]
	v_mfma_f32_16x16x32_bf16 v[18:21], v[76:79], v[60:63], v[18:21]
	v_mfma_f32_16x16x32_bf16 v[2:5], v[76:79], v[64:67], v[2:5]
	s_nop 1
	s_branch .LBB0_1110

.LBB0_1379:
	s_ashr_i32 s11, s10, 31
	s_lshl_b64 s[20:21], s[10:11], 1
	v_lshl_add_u64 v[140:141], v[46:47], 0, s[20:21]
	s_mov_b32 s99, 0
	s_mov_b32 s98, s13
	v_lshl_add_u64 v[142:143], v[140:141], 0, s[98:99]
	s_mov_b32 s98, s14
	v_lshl_add_u64 v[144:145], v[140:141], 0, s[98:99]
	s_mov_b32 s98, s15
	v_lshl_add_u64 v[146:147], v[140:141], 0, s[98:99]
	v_lshl_add_u64 v[148:149], v[36:37], 0, s[20:21]
	v_lshl_add_u64 v[150:151], v[148:149], 0, v[44:45]
	v_lshl_add_u64 v[148:149], v[148:149], 0, v[42:43]
	global_load_dwordx4 v[180:183], v[140:141], off
	global_load_dwordx4 v[184:187], v[148:149], off
	global_load_dwordx4 v[188:191], v[150:151], off
	global_load_dwordx4 v[192:195], v[142:143], off
	global_load_dwordx4 v[196:199], v[144:145], off
	global_load_dwordx4 v[200:203], v[146:147], off
	global_load_dwordx4 v[204:207], v[140:141], off offset:512
	global_load_dwordx4 v[208:211], v[148:149], off offset:512
	global_load_dwordx4 v[212:215], v[150:151], off offset:512
	global_load_dwordx4 v[216:219], v[142:143], off offset:512
	global_load_dwordx4 v[220:223], v[144:145], off offset:512
	global_load_dwordx4 v[224:227], v[146:147], off offset:512
	global_load_dwordx4 v[116:119], v[140:141], off offset:1024
	global_load_dwordx4 v[120:123], v[148:149], off offset:1024
	global_load_dwordx4 v[124:127], v[150:151], off offset:1024
	global_load_dwordx4 v[128:131], v[142:143], off offset:1024
	global_load_dwordx4 v[132:135], v[144:145], off offset:1024
	global_load_dwordx4 v[136:139], v[146:147], off offset:1024
	global_load_dwordx4 v[56:59], v[140:141], off offset:1536
	global_load_dwordx4 v[60:63], v[148:149], off offset:1536
	global_load_dwordx4 v[64:67], v[150:151], off offset:1536
	global_load_dwordx4 v[68:71], v[142:143], off offset:1536
	global_load_dwordx4 v[72:75], v[144:145], off offset:1536
	global_load_dwordx4 v[76:79], v[146:147], off offset:1536
	s_waitcnt vmcnt(18)
	v_mfma_f32_16x16x32_bf16 v[26:29], v[192:195], v[184:187], v[26:29]
	v_mfma_f32_16x16x32_bf16 v[30:33], v[180:183], v[184:187], v[30:33]
	v_mfma_f32_16x16x32_bf16 v[14:17], v[180:183], v[188:191], v[14:17]
	v_mfma_f32_16x16x32_bf16 v[22:25], v[196:199], v[184:187], v[22:25]
	v_mfma_f32_16x16x32_bf16 v[10:13], v[192:195], v[188:191], v[10:13]
	v_mfma_f32_16x16x32_bf16 v[6:9], v[196:199], v[188:191], v[6:9]
	v_mfma_f32_16x16x32_bf16 v[18:21], v[200:203], v[184:187], v[18:21]
	v_mfma_f32_16x16x32_bf16 v[2:5], v[200:203], v[188:191], v[2:5]
	global_load_dwordx4 v[180:183], v[140:141], off offset:2048
	global_load_dwordx4 v[184:187], v[148:149], off offset:2048
	global_load_dwordx4 v[188:191], v[150:151], off offset:2048
	global_load_dwordx4 v[192:195], v[142:143], off offset:2048
	global_load_dwordx4 v[196:199], v[144:145], off offset:2048
	global_load_dwordx4 v[200:203], v[146:147], off offset:2048
	s_waitcnt vmcnt(18)
	v_mfma_f32_16x16x32_bf16 v[26:29], v[216:219], v[208:211], v[26:29]
	v_mfma_f32_16x16x32_bf16 v[30:33], v[204:207], v[208:211], v[30:33]
	v_mfma_f32_16x16x32_bf16 v[14:17], v[204:207], v[212:215], v[14:17]
	v_mfma_f32_16x16x32_bf16 v[22:25], v[220:223], v[208:211], v[22:25]
	v_mfma_f32_16x16x32_bf16 v[10:13], v[216:219], v[212:215], v[10:13]
	v_mfma_f32_16x16x32_bf16 v[6:9], v[220:223], v[212:215], v[6:9]
	v_mfma_f32_16x16x32_bf16 v[18:21], v[224:227], v[208:211], v[18:21]
	v_mfma_f32_16x16x32_bf16 v[2:5], v[224:227], v[212:215], v[2:5]
	global_load_dwordx4 v[204:207], v[140:141], off offset:2560
	global_load_dwordx4 v[208:211], v[148:149], off offset:2560
	global_load_dwordx4 v[212:215], v[150:151], off offset:2560
	global_load_dwordx4 v[216:219], v[142:143], off offset:2560
	global_load_dwordx4 v[220:223], v[144:145], off offset:2560
	global_load_dwordx4 v[224:227], v[146:147], off offset:2560
	s_waitcnt vmcnt(18)
	v_mfma_f32_16x16x32_bf16 v[26:29], v[128:131], v[120:123], v[26:29]
	v_mfma_f32_16x16x32_bf16 v[30:33], v[116:119], v[120:123], v[30:33]
	v_mfma_f32_16x16x32_bf16 v[14:17], v[116:119], v[124:127], v[14:17]
	v_mfma_f32_16x16x32_bf16 v[22:25], v[132:135], v[120:123], v[22:25]
	v_mfma_f32_16x16x32_bf16 v[10:13], v[128:131], v[124:127], v[10:13]
	v_mfma_f32_16x16x32_bf16 v[6:9], v[132:135], v[124:127], v[6:9]
	v_mfma_f32_16x16x32_bf16 v[18:21], v[136:139], v[120:123], v[18:21]
	v_mfma_f32_16x16x32_bf16 v[2:5], v[136:139], v[124:127], v[2:5]
	global_load_dwordx4 v[116:119], v[140:141], off offset:3072
	global_load_dwordx4 v[120:123], v[148:149], off offset:3072
	global_load_dwordx4 v[124:127], v[150:151], off offset:3072
	global_load_dwordx4 v[128:131], v[142:143], off offset:3072
	global_load_dwordx4 v[132:135], v[144:145], off offset:3072
	global_load_dwordx4 v[136:139], v[146:147], off offset:3072
	s_waitcnt vmcnt(18)
	v_mfma_f32_16x16x32_bf16 v[26:29], v[68:71], v[60:63], v[26:29]
	v_mfma_f32_16x16x32_bf16 v[30:33], v[56:59], v[60:63], v[30:33]
	v_mfma_f32_16x16x32_bf16 v[14:17], v[56:59], v[64:67], v[14:17]
	v_mfma_f32_16x16x32_bf16 v[22:25], v[72:75], v[60:63], v[22:25]
	v_mfma_f32_16x16x32_bf16 v[10:13], v[68:71], v[64:67], v[10:13]
	v_mfma_f32_16x16x32_bf16 v[6:9], v[72:75], v[64:67], v[6:9]
	v_mfma_f32_16x16x32_bf16 v[18:21], v[76:79], v[60:63], v[18:21]
	v_mfma_f32_16x16x32_bf16 v[2:5], v[76:79], v[64:67], v[2:5]
	global_load_dwordx4 v[56:59], v[140:141], off offset:3584
	global_load_dwordx4 v[60:63], v[148:149], off offset:3584
	global_load_dwordx4 v[64:67], v[150:151], off offset:3584
	global_load_dwordx4 v[68:71], v[142:143], off offset:3584
	global_load_dwordx4 v[72:75], v[144:145], off offset:3584
	global_load_dwordx4 v[76:79], v[146:147], off offset:3584
	s_waitcnt vmcnt(18)
	v_mfma_f32_16x16x32_bf16 v[26:29], v[192:195], v[184:187], v[26:29]
	v_mfma_f32_16x16x32_bf16 v[30:33], v[180:183], v[184:187], v[30:33]
	v_mfma_f32_16x16x32_bf16 v[14:17], v[180:183], v[188:191], v[14:17]
	v_mfma_f32_16x16x32_bf16 v[22:25], v[196:199], v[184:187], v[22:25]
	v_mfma_f32_16x16x32_bf16 v[10:13], v[192:195], v[188:191], v[10:13]
	v_mfma_f32_16x16x32_bf16 v[6:9], v[196:199], v[188:191], v[6:9]
	v_mfma_f32_16x16x32_bf16 v[18:21], v[200:203], v[184:187], v[18:21]
	v_mfma_f32_16x16x32_bf16 v[2:5], v[200:203], v[188:191], v[2:5]
	s_movk_i32 s98, 0x1000
	v_lshl_add_u64 v[140:141], v[140:141], 0, s[98:99]
	v_lshl_add_u64 v[142:143], v[142:143], 0, s[98:99]
	v_lshl_add_u64 v[144:145], v[144:145], 0, s[98:99]
	v_lshl_add_u64 v[146:147], v[146:147], 0, s[98:99]
	v_lshl_add_u64 v[148:149], v[148:149], 0, s[98:99]
	v_lshl_add_u64 v[150:151], v[150:151], 0, s[98:99]
	global_load_dwordx4 v[180:183], v[140:141], off
	global_load_dwordx4 v[184:187], v[148:149], off
	global_load_dwordx4 v[188:191], v[150:151], off
	global_load_dwordx4 v[192:195], v[142:143], off
	global_load_dwordx4 v[196:199], v[144:145], off
	global_load_dwordx4 v[200:203], v[146:147], off
	s_waitcnt vmcnt(18)
	v_mfma_f32_16x16x32_bf16 v[26:29], v[216:219], v[208:211], v[26:29]
	v_mfma_f32_16x16x32_bf16 v[30:33], v[204:207], v[208:211], v[30:33]
	v_mfma_f32_16x16x32_bf16 v[14:17], v[204:207], v[212:215], v[14:17]
	v_mfma_f32_16x16x32_bf16 v[22:25], v[220:223], v[208:211], v[22:25]
	v_mfma_f32_16x16x32_bf16 v[10:13], v[216:219], v[212:215], v[10:13]
	v_mfma_f32_16x16x32_bf16 v[6:9], v[220:223], v[212:215], v[6:9]
	v_mfma_f32_16x16x32_bf16 v[18:21], v[224:227], v[208:211], v[18:21]
	v_mfma_f32_16x16x32_bf16 v[2:5], v[224:227], v[212:215], v[2:5]
	global_load_dwordx4 v[204:207], v[140:141], off offset:512
	global_load_dwordx4 v[208:211], v[148:149], off offset:512
	global_load_dwordx4 v[212:215], v[150:151], off offset:512
	global_load_dwordx4 v[216:219], v[142:143], off offset:512
	global_load_dwordx4 v[220:223], v[144:145], off offset:512
	global_load_dwordx4 v[224:227], v[146:147], off offset:512
	s_waitcnt vmcnt(18)
	v_mfma_f32_16x16x32_bf16 v[26:29], v[128:131], v[120:123], v[26:29]
	v_mfma_f32_16x16x32_bf16 v[30:33], v[116:119], v[120:123], v[30:33]
	v_mfma_f32_16x16x32_bf16 v[14:17], v[116:119], v[124:127], v[14:17]
	v_mfma_f32_16x16x32_bf16 v[22:25], v[132:135], v[120:123], v[22:25]
	v_mfma_f32_16x16x32_bf16 v[10:13], v[128:131], v[124:127], v[10:13]
	v_mfma_f32_16x16x32_bf16 v[6:9], v[132:135], v[124:127], v[6:9]
	v_mfma_f32_16x16x32_bf16 v[18:21], v[136:139], v[120:123], v[18:21]
	v_mfma_f32_16x16x32_bf16 v[2:5], v[136:139], v[124:127], v[2:5]
	global_load_dwordx4 v[116:119], v[140:141], off offset:1024
	global_load_dwordx4 v[120:123], v[148:149], off offset:1024
	global_load_dwordx4 v[124:127], v[150:151], off offset:1024
	global_load_dwordx4 v[128:131], v[142:143], off offset:1024
	global_load_dwordx4 v[132:135], v[144:145], off offset:1024
	global_load_dwordx4 v[136:139], v[146:147], off offset:1024
	s_waitcnt vmcnt(18)
	v_mfma_f32_16x16x32_bf16 v[26:29], v[68:71], v[60:63], v[26:29]
	v_mfma_f32_16x16x32_bf16 v[30:33], v[56:59], v[60:63], v[30:33]
	v_mfma_f32_16x16x32_bf16 v[14:17], v[56:59], v[64:67], v[14:17]
	v_mfma_f32_16x16x32_bf16 v[22:25], v[72:75], v[60:63], v[22:25]
	v_mfma_f32_16x16x32_bf16 v[10:13], v[68:71], v[64:67], v[10:13]
	v_mfma_f32_16x16x32_bf16 v[6:9], v[72:75], v[64:67], v[6:9]
	v_mfma_f32_16x16x32_bf16 v[18:21], v[76:79], v[60:63], v[18:21]
	v_mfma_f32_16x16x32_bf16 v[2:5], v[76:79], v[64:67], v[2:5]
	s_waitcnt vmcnt(12)
	v_mfma_f32_16x16x32_bf16 v[26:29], v[192:195], v[184:187], v[26:29]
	v_mfma_f32_16x16x32_bf16 v[30:33], v[180:183], v[184:187], v[30:33]
	v_mfma_f32_16x16x32_bf16 v[14:17], v[180:183], v[188:191], v[14:17]
	v_mfma_f32_16x16x32_bf16 v[22:25], v[196:199], v[184:187], v[22:25]
	v_mfma_f32_16x16x32_bf16 v[10:13], v[192:195], v[188:191], v[10:13]
	v_mfma_f32_16x16x32_bf16 v[6:9], v[196:199], v[188:191], v[6:9]
	v_mfma_f32_16x16x32_bf16 v[18:21], v[200:203], v[184:187], v[18:21]
	v_mfma_f32_16x16x32_bf16 v[2:5], v[200:203], v[188:191], v[2:5]
	s_waitcnt vmcnt(6)
	v_mfma_f32_16x16x32_bf16 v[26:29], v[216:219], v[208:211], v[26:29]
	v_mfma_f32_16x16x32_bf16 v[30:33], v[204:207], v[208:211], v[30:33]
	v_mfma_f32_16x16x32_bf16 v[14:17], v[204:207], v[212:215], v[14:17]
	v_mfma_f32_16x16x32_bf16 v[22:25], v[220:223], v[208:211], v[22:25]
	v_mfma_f32_16x16x32_bf16 v[10:13], v[216:219], v[212:215], v[10:13]
	v_mfma_f32_16x16x32_bf16 v[6:9], v[220:223], v[212:215], v[6:9]
	v_mfma_f32_16x16x32_bf16 v[18:21], v[224:227], v[208:211], v[18:21]
	v_mfma_f32_16x16x32_bf16 v[2:5], v[224:227], v[212:215], v[2:5]
	s_waitcnt vmcnt(0)
	v_mfma_f32_16x16x32_bf16 v[26:29], v[128:131], v[120:123], v[26:29]
	v_mfma_f32_16x16x32_bf16 v[30:33], v[116:119], v[120:123], v[30:33]
	v_mfma_f32_16x16x32_bf16 v[14:17], v[116:119], v[124:127], v[14:17]
	v_mfma_f32_16x16x32_bf16 v[22:25], v[132:135], v[120:123], v[22:25]
	v_mfma_f32_16x16x32_bf16 v[10:13], v[128:131], v[124:127], v[10:13]
	v_mfma_f32_16x16x32_bf16 v[6:9], v[132:135], v[124:127], v[6:9]
	v_mfma_f32_16x16x32_bf16 v[18:21], v[136:139], v[120:123], v[18:21]
	v_mfma_f32_16x16x32_bf16 v[2:5], v[136:139], v[124:127], v[2:5]
	s_nop 1
	s_branch .LBB0_1376
